# v004 plus: waves 4-7 skip their duplicate fp8-K LDS-DMA in the mixer-A loop (waves 0-3 already stage all four pieces), end-of-step wait vmcnt(2)
# baseline (speedup 1.0000x reference)
; #define LAS __attribute__((address_space(3)))
; __device__ __forceinline__ unsigned xb_add(unsigned* p, unsigned v) { return __hip_atomic_fetch_add(p, v, __ATOMIC_RELAXED, __HIP_MEMORY_SCOPE_AGENT); }
; __device__ __forceinline__ unsigned xb_xcc_id() { return (unsigned)__builtin_amdgcn_s_getreg((3 << 11) | 20) & 0xFu; }
; __device__ __forceinline__ XcdBarrier xcd_barrier_post(unsigned* bar, volatile LAS unsigned* st) {
;     XcdBarrier b; b.bar = bar; b.x = (unsigned)__builtin_amdgcn_readfirstlane((int)xb_xcc_id()); b.st = st;
;     if (threadIdx.x == 0) (void)xb_add(&bar[XB_XCNT(b.x)], 1u);
;     return b;
; }
; __global__ void __launch_bounds__(512, 2) mk_fwd(Args args) {
;     extern __shared__ __attribute__((aligned(16))) unsigned char lds[];
;     cg::grid_group grid = cg::this_grid();
;     volatile LAS unsigned* bst = (volatile LAS unsigned*)((LAS unsigned char*)lds + (LDS_BYTES - 64));
;     if (threadIdx.x < 2) bst[threadIdx.x] = 0u;
;     __syncthreads();
;     const XcdBarrier xbar = xcd_barrier_post((unsigned*)(args.ws + WS_BAR), bst);
_Z6mk_fwd4Args:
	v_readfirstlane_b32 s100, v0
	s_bfe_u32 s100, s100, 0x10008
	s_add_u32 s64, s0, 0x130
	v_writelane_b32 v252, s2, 0
	s_load_dwordx2 s[62:63], s[0:1], 0x130
	s_load_dword s2, s[0:1], 0x138
	v_writelane_b32 v252, s0, 1
	v_and_b32_e32 v238, 0x3ff, v0
	s_addc_u32 s65, s1, 0
	v_writelane_b32 v252, s1, 2
	v_cmp_gt_u32_e32 vcc, 2, v238
	s_and_saveexec_b64 s[4:5], vcc
	v_lshl_add_u32 v1, v238, 2, 0
	v_add_u32_e32 v1, 0x23fc0, v1
	v_mov_b32_e32 v2, 0
	ds_write_b32 v1, v2
	s_or_b64 exec, exec, s[4:5]
	v_readlane_b32 s0, v252, 1
	v_readlane_b32 s1, v252, 2
	s_load_dwordx2 s[84:85], s[0:1], 0xb8
	s_waitcnt lgkmcnt(0)
	s_barrier
	s_getreg_b32 s3, hwreg(HW_REG_XCC_ID, 0, 4)
	s_add_u32 s86, s84, 0x310000
	s_addc_u32 s87, s85, 0
	s_and_b32 s0, s3, 15
	v_writelane_b32 v252, s0, 3
	v_cmp_eq_u32_e64 s[0:1], 0, v238
	s_nop 1
	v_writelane_b32 v252, s0, 4
	s_nop 1
	v_writelane_b32 v252, s1, 5
	s_and_saveexec_b64 s[4:5], s[0:1]
	s_cbranch_execz .LBB0_5
	s_mov_b64 s[6:7], exec
	v_mbcnt_lo_u32_b32 v1, s6, 0
	v_mbcnt_hi_u32_b32 v1, s7, v1
	v_cmp_eq_u32_e32 vcc, 0, v1
	s_and_b64 s[8:9], exec, vcc
	s_mov_b64 exec, s[8:9]
	s_cbranch_execz .LBB0_5
	v_readlane_b32 s0, v252, 3
	s_lshl_b32 s3, s0, 8
	s_bcnt1_i32_b64 s6, s[6:7]
	v_mov_b32_e32 v1, s3
	v_mov_b32_e32 v2, s6
	global_atomic_add v1, v2, s[86:87] offset:1024

; #define WAIT_BAR(N) asm volatile("s_waitcnt vmcnt(" #N ") lgkmcnt(0)\n\ts_barrier":::"memory")
;   #define RESC() do{ if(resc){ asm volatile("s_waitcnt lgkmcnt(0)":::"memory"); \
;       _Pragma("unroll") for(int d_=0;d_<2;++d_) _Pragma("unroll") for(int r=0;r<16;++r)o[d_][r]*=wsf[crow(r,hi)]; } }while(0)
;   #define ROT() do{sl_prev=sl_cur;sl_cur=sl_next;sl_next=(sl_next==(NSLOT-1)*SLOTB)?0:sl_next+SLOTB;}while(0)
; #define WAIT_BAR(N) asm volatile("s_waitcnt vmcnt(" #N ") lgkmcnt(0)\n\ts_barrier":::"memory")
;   #define RESC() do{ if(resc){ asm volatile("s_waitcnt lgkmcnt(0)":::"memory"); \
;       _Pragma("unroll") for(int d_=0;d_<4;++d_) _Pragma("unroll") for(int r=0;r<16;++r)o[d_][r]*=wsf[crow(r,hi)]; } }while(0)
;   #define ROT() do{sl_prev=sl_cur;sl_cur=sl_next;sl_next=(sl_next==(NSLOT-1)*SLOTB)?0:sl_next+SLOTB;}while(0)
; #define WAIT_BAR(N) asm volatile("s_waitcnt vmcnt(" #N ") lgkmcnt(0)\n\ts_barrier":::"memory")
;   #define RESC() do{ if(resc){ asm volatile("s_waitcnt lgkmcnt(0)":::"memory"); \
;       _Pragma("unroll") for(int d_=0;d_<2;++d_) _Pragma("unroll") for(int r=0;r<16;++r)o[d_][r]*=wsf[crow(r,hi)]; } }while(0)
;   #define ROT() do{sl_prev=sl_cur;sl_cur=sl_next;sl_next=(sl_next==(NSLOT-1)*SLOTB)?0:sl_next+SLOTB;}while(0)
; template<int THRL,bool FIXED> __device__ __forceinline__ void attn_unit(int qb,const bf16*Qp,const unsigned char*__restrict__ K8h,const bf16*__restrict__ Vh,bf16*Op,int PO,char*shm){
;     ...
;   int t=1;
;     ...
;   for(;t+5<NT;t+=2){
;     STEP(pB0,pB1,pA0,pA1,t,true,true,true);     WAIT_BAR(3); RESC(); ROT();
;     STEP(pA0,pA1,pB0,pB1,t+1,true,true,true);   WAIT_BAR(3); RESC(); ROT();
.LBB0_543:
	s_add_i32 s22, s10, 0x8000
	s_and_b32 s22, s22, 0x6000
	v_add_u32_e32 v116, s22, v166
	ds_read_b64_tr_b16 v[120:121], v116 offset:24576
	ds_read_b64_tr_b16 v[122:123], v116 offset:25088
	s_add_i32 s23, s10, 0x2000
	v_add_f32_e32 v96, v64, v65
	v_add_f32_e32 v96, v66, v96
	v_add_f32_e32 v96, v67, v96
	v_add_f32_e32 v96, v68, v96
	v_add_f32_e32 v117, v69, v96
	v_cvt_pk_bf16_f32 v148, v64, v65
	v_cvt_pk_bf16_f32 v149, v66, v67
	v_mfma_scale_f32_32x32x64_f8f6f4 v[96:111], v[88:95], v[128:135], v[32:47], v242, v241 op_sel_hi:[0,0,0]
	ds_read_b64_tr_b16 v[64:65], v116 offset:28672
	ds_read_b64_tr_b16 v[66:67], v116 offset:29184
	v_add_f32_e32 v88, v70, v117
	v_add_f32_e32 v88, v71, v88
	v_add_f32_e32 v88, v72, v88
	v_add_f32_e32 v117, v73, v88
	v_mfma_scale_f32_32x32x64_f8f6f4 v[80:95], v[80:87], v[128:135], v[32:47], v242, v241 op_sel_hi:[0,0,0]
	v_cvt_pk_bf16_f32 v150, v68, v69
	v_cvt_pk_bf16_f32 v151, v70, v71
	ds_read_b64_tr_b16 v[68:69], v116 offset:25600
	ds_read_b64_tr_b16 v[70:71], v116 offset:26112
	v_add_f32_e32 v117, v74, v117
	v_add_f32_e32 v117, v75, v117
	v_add_f32_e32 v117, v76, v117
	v_add_f32_e32 v117, v77, v117
	v_cvt_pk_bf16_f32 v144, v72, v73
	v_cvt_pk_bf16_f32 v145, v74, v75
	ds_read_b64_tr_b16 v[72:73], v116 offset:29696
	ds_read_b64_tr_b16 v[74:75], v116 offset:30208
	v_add_f32_e32 v117, v78, v117
	v_add_f32_e32 v117, v79, v117
	v_add_f32_e32 v117, v48, v117
	v_add_f32_e32 v117, v49, v117
	v_cvt_pk_bf16_f32 v146, v76, v77
	v_cvt_pk_bf16_f32 v147, v78, v79
	ds_read_b64_tr_b16 v[76:77], v116 offset:26624
	ds_read_b64_tr_b16 v[78:79], v116 offset:27136
	v_add_f32_e32 v117, v50, v117
	v_add_f32_e32 v117, v51, v117
	v_add_f32_e32 v117, v52, v117
	v_add_f32_e32 v117, v53, v117
	v_cvt_pk_bf16_f32 v140, v48, v49
	v_cvt_pk_bf16_f32 v141, v50, v51
	ds_read_b64_tr_b16 v[124:125], v116 offset:30720
	ds_read_b64_tr_b16 v[126:127], v116 offset:31232
	v_add_f32_e32 v48, v54, v117
	v_add_f32_e32 v48, v55, v48
	v_add_f32_e32 v48, v56, v48
	v_add_f32_e32 v48, v57, v48
	v_cvt_pk_bf16_f32 v142, v52, v53
	v_cvt_pk_bf16_f32 v143, v54, v55
	ds_read_b64_tr_b16 v[168:169], v116 offset:27648
	ds_read_b64_tr_b16 v[170:171], v116 offset:28160
	v_add_f32_e32 v48, v58, v48
	v_add_f32_e32 v48, v59, v48
	v_add_f32_e32 v48, v60, v48
	v_add_f32_e32 v48, v61, v48
	v_cvt_pk_bf16_f32 v136, v56, v57
	v_cvt_pk_bf16_f32 v137, v58, v59
	ds_read_b64_tr_b16 v[172:173], v116 offset:31744
	ds_read_b64_tr_b16 v[174:175], v116 offset:32256
	v_add_f32_e32 v48, v62, v48
	v_add_f32_e32 v48, v63, v48
	v_add_f32_e32 v119, v118, v48
	v_cvt_pk_bf16_f32 v138, v60, v61
	v_cvt_pk_bf16_f32 v139, v62, v63
	s_cmp_lg_u32 s100, 0
	s_cbranch_scc1 .Lska1
	v_lshl_add_u64 v[116:117], v[114:115], 0, s[10:11]
	s_add_i32 s50, s50, s29
	s_mov_b32 m0, s50
	v_lshl_add_u64 v[48:49], v[116:117], 0, s[60:61]
	global_load_lds_dwordx4 v[48:49], off
.Lska1:
	s_add_i32 s50, s10, 0x6000
	s_and_b32 s50, s50, 0x6000
	s_add_i32 s50, s50, s44
	s_mov_b32 m0, s50
	v_lshl_add_u64 v[48:49], v[112:113], 0, s[36:37]
	global_load_lds_dwordx4 v[48:49], off
	s_waitcnt lgkmcnt(8)
	v_mfma_f32_32x32x16_bf16 v[0:15], v[148:151], v[120:123], v[0:15]
	v_exp_f32_e32 v96, v96
	v_exp_f32_e32 v97, v97
	v_exp_f32_e32 v98, v98
	v_exp_f32_e32 v99, v99
	v_mfma_f32_32x32x16_bf16 v[16:31], v[148:151], v[64:67], v[16:31]
	v_exp_f32_e32 v100, v100
	v_exp_f32_e32 v101, v101
	v_exp_f32_e32 v102, v102
	v_exp_f32_e32 v103, v103
	v_add_u32_e32 v60, s13, v165
	ds_read_b128 v[48:51], v60
	v_mfma_f32_32x32x16_bf16 v[0:15], v[144:147], v[68:71], v[0:15]
	v_exp_f32_e32 v104, v104
	v_exp_f32_e32 v105, v105
	v_exp_f32_e32 v106, v106
	v_exp_f32_e32 v107, v107
	ds_read_b128 v[52:55], v60 offset:1024
	v_mfma_f32_32x32x16_bf16 v[16:31], v[144:147], v[72:75], v[16:31]
	v_exp_f32_e32 v108, v108
	v_exp_f32_e32 v109, v109
	v_exp_f32_e32 v110, v110
	v_exp_f32_e32 v111, v111
	ds_read_b128 v[56:59], v60 offset:512
	s_waitcnt lgkmcnt(3)
	v_mfma_f32_32x32x16_bf16 v[0:15], v[140:143], v[76:79], v[0:15]
	v_exp_f32_e32 v80, v80
	v_exp_f32_e32 v81, v81
	v_exp_f32_e32 v82, v82
	v_exp_f32_e32 v83, v83
	ds_read_b128 v[60:63], v60 offset:1536
	v_mfma_f32_32x32x16_bf16 v[16:31], v[140:143], v[124:127], v[16:31]
	v_exp_f32_e32 v84, v84
	v_exp_f32_e32 v85, v85
	v_exp_f32_e32 v86, v86
	v_exp_f32_e32 v87, v87
	v_mfma_f32_32x32x16_bf16 v[0:15], v[136:139], v[168:171], v[0:15]
	v_exp_f32_e32 v88, v88
	v_exp_f32_e32 v89, v89
	v_exp_f32_e32 v90, v90
	v_exp_f32_e32 v91, v91
	v_mfma_f32_32x32x16_bf16 v[16:31], v[136:139], v[172:175], v[16:31]
	v_exp_f32_e32 v92, v92
	v_exp_f32_e32 v93, v93
	v_exp_f32_e32 v94, v94
	v_exp_f32_e32 v95, v95
	s_waitcnt vmcnt(2) lgkmcnt(0)
	s_barrier
; #define WAIT_BAR(N) asm volatile("s_waitcnt vmcnt(" #N ") lgkmcnt(0)\n\ts_barrier":::"memory")
;   #define RESC() do{ if(resc){ asm volatile("s_waitcnt lgkmcnt(0)":::"memory"); \
;       _Pragma("unroll") for(int d_=0;d_<2;++d_) _Pragma("unroll") for(int r=0;r<16;++r)o[d_][r]*=wsf[crow(r,hi)]; } }while(0)
;   #define ROT() do{sl_prev=sl_cur;sl_cur=sl_next;sl_next=(sl_next==(NSLOT-1)*SLOTB)?0:sl_next+SLOTB;}while(0)
; #define WAIT_BAR(N) asm volatile("s_waitcnt vmcnt(" #N ") lgkmcnt(0)\n\ts_barrier":::"memory")
;   #define RESC() do{ if(resc){ asm volatile("s_waitcnt lgkmcnt(0)":::"memory"); \
;       _Pragma("unroll") for(int d_=0;d_<4;++d_) _Pragma("unroll") for(int r=0;r<16;++r)o[d_][r]*=wsf[crow(r,hi)]; } }while(0)
;   #define ROT() do{sl_prev=sl_cur;sl_cur=sl_next;sl_next=(sl_next==(NSLOT-1)*SLOTB)?0:sl_next+SLOTB;}while(0)
; #define WAIT_BAR(N) asm volatile("s_waitcnt vmcnt(" #N ") lgkmcnt(0)\n\ts_barrier":::"memory")
;   #define RESC() do{ if(resc){ asm volatile("s_waitcnt lgkmcnt(0)":::"memory"); \
;       _Pragma("unroll") for(int d_=0;d_<2;++d_) _Pragma("unroll") for(int r=0;r<16;++r)o[d_][r]*=wsf[crow(r,hi)]; } }while(0)
;   #define ROT() do{sl_prev=sl_cur;sl_cur=sl_next;sl_next=(sl_next==(NSLOT-1)*SLOTB)?0:sl_next+SLOTB;}while(0)
; template<int THRL,bool FIXED> __device__ __forceinline__ void attn_unit(int qb,const bf16*Qp,const unsigned char*__restrict__ K8h,const bf16*__restrict__ Vh,bf16*Op,int PO,char*shm){
;     ...
;   int t=1;
;     ...
;   for(;t+5<NT;t+=2){
;     STEP(pB0,pB1,pA0,pA1,t,true,true,true);     WAIT_BAR(3); RESC(); ROT();
;     STEP(pA0,pA1,pB0,pB1,t+1,true,true,true);   WAIT_BAR(3); RESC(); ROT();
	s_add_i32 s50, s13, 0x2000
	s_cmpk_lg_i32 s13, 0x4000
	s_cselect_b32 s50, s50, 0
	s_and_b32 s23, s23, 0x6000
	v_add_u32_e32 v160, s23, v166
	ds_read_b64_tr_b16 v[120:121], v160 offset:24576
	ds_read_b64_tr_b16 v[122:123], v160 offset:25088
	v_add_f32_e32 v64, v96, v97
	v_add_f32_e32 v64, v98, v64
	v_add_f32_e32 v64, v99, v64
	v_add_f32_e32 v64, v100, v64
	v_add_f32_e32 v124, v101, v64
	v_mfma_scale_f32_32x32x64_f8f6f4 v[64:79], v[48:55], v[128:135], v[32:47], v242, v241 op_sel_hi:[0,0,0]
	v_cvt_pk_bf16_f32 v148, v96, v97
	v_cvt_pk_bf16_f32 v149, v98, v99
	ds_read_b64_tr_b16 v[96:97], v160 offset:28672
	ds_read_b64_tr_b16 v[98:99], v160 offset:29184
	v_add_f32_e32 v48, v102, v124
	v_add_f32_e32 v48, v103, v48
	v_add_f32_e32 v48, v104, v48
	v_add_f32_e32 v124, v105, v48
	v_mfma_scale_f32_32x32x64_f8f6f4 v[48:63], v[56:63], v[128:135], v[32:47], v242, v241 op_sel_hi:[0,0,0]
	v_cvt_pk_bf16_f32 v150, v100, v101
	v_cvt_pk_bf16_f32 v151, v102, v103
	ds_read_b64_tr_b16 v[100:101], v160 offset:25600
	ds_read_b64_tr_b16 v[102:103], v160 offset:26112
	v_add_f32_e32 v124, v106, v124
	v_add_f32_e32 v124, v107, v124
	v_add_f32_e32 v124, v108, v124
	v_add_f32_e32 v124, v109, v124
	v_cvt_pk_bf16_f32 v144, v104, v105
	v_cvt_pk_bf16_f32 v145, v106, v107
	ds_read_b64_tr_b16 v[104:105], v160 offset:29696
	ds_read_b64_tr_b16 v[106:107], v160 offset:30208
	v_add_f32_e32 v124, v110, v124
	v_add_f32_e32 v124, v111, v124
	v_add_f32_e32 v124, v80, v124
	v_add_f32_e32 v124, v81, v124
	v_cvt_pk_bf16_f32 v146, v108, v109
	v_cvt_pk_bf16_f32 v147, v110, v111
	ds_read_b64_tr_b16 v[108:109], v160 offset:26624
	ds_read_b64_tr_b16 v[110:111], v160 offset:27136
	v_add_f32_e32 v124, v82, v124
	v_add_f32_e32 v124, v83, v124
	v_add_f32_e32 v124, v84, v124
	v_add_f32_e32 v136, v85, v124
	v_cvt_pk_bf16_f32 v140, v80, v81
	v_cvt_pk_bf16_f32 v141, v82, v83
	ds_read_b64_tr_b16 v[124:125], v160 offset:30720
	ds_read_b64_tr_b16 v[126:127], v160 offset:31232
	v_add_f32_e32 v80, v86, v136
	v_add_f32_e32 v80, v87, v80
	v_add_f32_e32 v80, v88, v80
	v_add_f32_e32 v80, v89, v80
	v_cvt_pk_bf16_f32 v142, v84, v85
	v_cvt_pk_bf16_f32 v143, v86, v87
	ds_read_b64_tr_b16 v[168:169], v160 offset:27648
	ds_read_b64_tr_b16 v[170:171], v160 offset:28160
	v_add_f32_e32 v80, v90, v80
	v_add_f32_e32 v80, v91, v80
	v_add_f32_e32 v80, v92, v80
	v_add_f32_e32 v80, v93, v80
	v_cvt_pk_bf16_f32 v136, v88, v89
	v_cvt_pk_bf16_f32 v137, v90, v91
	ds_read_b64_tr_b16 v[172:173], v160 offset:31744
	ds_read_b64_tr_b16 v[174:175], v160 offset:32256
	v_add_f32_e32 v80, v94, v80
	v_add_f32_e32 v80, v95, v80
	v_add_f32_e32 v118, v119, v80
	v_cvt_pk_bf16_f32 v138, v92, v93
	v_cvt_pk_bf16_f32 v139, v94, v95
	s_cmp_lg_u32 s100, 0
	s_cbranch_scc1 .Lska2
	s_add_i32 s13, s13, s29
	s_mov_b32 m0, s13
	v_lshl_add_u64 v[80:81], v[116:117], 0, s[56:57]
	global_load_lds_dwordx4 v[80:81], off
.Lska2:
	s_add_i32 s13, s22, s44
	s_mov_b32 m0, s13
	s_nop 0
	global_load_lds_dwordx4 v[112:113], off
	s_waitcnt lgkmcnt(8)
	v_mfma_f32_32x32x16_bf16 v[0:15], v[148:151], v[120:123], v[0:15]
	v_exp_f32_e32 v64, v64
	v_exp_f32_e32 v65, v65
	v_exp_f32_e32 v66, v66
	v_exp_f32_e32 v67, v67
	v_mfma_f32_32x32x16_bf16 v[16:31], v[148:151], v[96:99], v[16:31]
	v_exp_f32_e32 v68, v68
	v_exp_f32_e32 v69, v69
	v_exp_f32_e32 v70, v70
	v_exp_f32_e32 v71, v71
	v_add_u32_e32 v84, s50, v165
	ds_read_b128 v[88:91], v84
	v_mfma_f32_32x32x16_bf16 v[0:15], v[144:147], v[100:103], v[0:15]
	v_exp_f32_e32 v72, v72
	v_exp_f32_e32 v73, v73
	v_exp_f32_e32 v74, v74
	v_exp_f32_e32 v75, v75
	ds_read_b128 v[92:95], v84 offset:1024
	v_mfma_f32_32x32x16_bf16 v[16:31], v[144:147], v[104:107], v[16:31]
	v_exp_f32_e32 v76, v76
	v_exp_f32_e32 v77, v77
	v_exp_f32_e32 v78, v78
	v_exp_f32_e32 v79, v79
	ds_read_b128 v[80:83], v84 offset:512
	s_waitcnt lgkmcnt(3)
	v_mfma_f32_32x32x16_bf16 v[0:15], v[140:143], v[108:111], v[0:15]
	v_exp_f32_e32 v48, v48
	v_exp_f32_e32 v49, v49
	v_exp_f32_e32 v50, v50
	v_exp_f32_e32 v51, v51
	ds_read_b128 v[84:87], v84 offset:1536
	v_mfma_f32_32x32x16_bf16 v[16:31], v[140:143], v[124:127], v[16:31]
	v_exp_f32_e32 v52, v52
	v_exp_f32_e32 v53, v53
	v_exp_f32_e32 v54, v54
	v_exp_f32_e32 v55, v55
	v_mfma_f32_32x32x16_bf16 v[0:15], v[136:139], v[168:171], v[0:15]
	v_exp_f32_e32 v56, v56
	v_exp_f32_e32 v57, v57
	v_exp_f32_e32 v58, v58
	v_exp_f32_e32 v59, v59
	v_mfma_f32_32x32x16_bf16 v[16:31], v[136:139], v[172:175], v[16:31]
	v_exp_f32_e32 v60, v60
	v_exp_f32_e32 v61, v61
	v_exp_f32_e32 v62, v62
	v_exp_f32_e32 v63, v63
	s_add_i32 s13, s50, 0x2000
	s_cmpk_lg_i32 s50, 0x4000
	s_cselect_b32 s13, s13, 0
	s_add_i32 s12, s12, 2
	s_waitcnt vmcnt(2) lgkmcnt(0)
	s_barrier
	s_add_u32 s10, s10, 0x4000
	s_addc_u32 s11, s11, 0
	v_lshl_add_u64 v[112:113], v[112:113], 0, s[40:41]
	s_cmpk_gt_u32 s12, 0xf8
	s_cbranch_scc0 .LBB0_543
; #define WAIT_BAR(N) asm volatile("s_waitcnt vmcnt(" #N ") lgkmcnt(0)\n\ts_barrier":::"memory")
;   #define RESC() do{ if(resc){ asm volatile("s_waitcnt lgkmcnt(0)":::"memory"); \
;       _Pragma("unroll") for(int d_=0;d_<2;++d_) _Pragma("unroll") for(int r=0;r<16;++r)o[d_][r]*=wsf[crow(r,hi)]; } }while(0)
;   #define ROT() do{sl_prev=sl_cur;sl_cur=sl_next;sl_next=(sl_next==(NSLOT-1)*SLOTB)?0:sl_next+SLOTB;}while(0)
;   #define ENDW(tt) do{ if((tt)+3<NT){WAIT_BAR(3);} else if((tt)+2<NT){WAIT_BAR(2);} else {WAIT_BAR(0);} }while(0)
; #define WAIT_BAR(N) asm volatile("s_waitcnt vmcnt(" #N ") lgkmcnt(0)\n\ts_barrier":::"memory")
;   #define RESC() do{ if(resc){ asm volatile("s_waitcnt lgkmcnt(0)":::"memory"); \
;       _Pragma("unroll") for(int d_=0;d_<4;++d_) _Pragma("unroll") for(int r=0;r<16;++r)o[d_][r]*=wsf[crow(r,hi)]; } }while(0)
;   #define ROT() do{sl_prev=sl_cur;sl_cur=sl_next;sl_next=(sl_next==(NSLOT-1)*SLOTB)?0:sl_next+SLOTB;}while(0)
;   #define ENDW(tt) do{ if((tt)+3<NT){WAIT_BAR(5);} else if((tt)+2<NT){WAIT_BAR(4);} else {WAIT_BAR(0);} }while(0)
; #define WAIT_BAR(N) asm volatile("s_waitcnt vmcnt(" #N ") lgkmcnt(0)\n\ts_barrier":::"memory")
;   #define RESC() do{ if(resc){ asm volatile("s_waitcnt lgkmcnt(0)":::"memory"); \
;       _Pragma("unroll") for(int d_=0;d_<2;++d_) _Pragma("unroll") for(int r=0;r<16;++r)o[d_][r]*=wsf[crow(r,hi)]; } }while(0)
;   #define ROT() do{sl_prev=sl_cur;sl_cur=sl_next;sl_next=(sl_next==(NSLOT-1)*SLOTB)?0:sl_next+SLOTB;}while(0)
;   #define ENDW(tt) do{ if((tt)+3<NT){WAIT_BAR(3);} else if((tt)+2<NT){WAIT_BAR(2);} else {WAIT_BAR(0);} }while(0)
; template<int THRL,bool FIXED> __device__ __forceinline__ void attn_unit(int qb,const bf16*Qp,const unsigned char*__restrict__ K8h,const bf16*__restrict__ Vh,bf16*Op,int PO,char*shm){
;     ...
;   int t=1;
;     ...
;   for(;t+5<NT;t+=2){
;     STEP(pB0,pB1,pA0,pA1,t,true,true,true);     WAIT_BAR(3); RESC(); ROT();
;     STEP(pA0,pA1,pB0,pB1,t+1,true,true,true);   WAIT_BAR(3); RESC(); ROT();
;   }
;     ...
;   for(;t+1<NT;t+=2){
;     STEP(pB0,pB1,pA0,pA1,t,(t+3<NT),(t+2<NT),(t+1<NT));       ENDW(t);   RESC(); ROT();
;     STEP(pA0,pA1,pB0,pB1,t+1,(t+4<NT),(t+3<NT),(t+2<NT));     ENDW(t+1); RESC(); ROT();
	s_mov_b32 m0, s101
	s_and_b32 s10, s34, 0x3fffffc0
	s_lshl_b32 s10, s10, 2
	s_add_i32 s12, s10, 0
	ds_read_b64_tr_b16 v[112:113], v166 offset:40960
	ds_read_b64_tr_b16 v[114:115], v166 offset:41472
	v_add_f32_e32 v96, v64, v65
	v_add_f32_e32 v96, v66, v96
	v_add_f32_e32 v96, v67, v96
	v_add_f32_e32 v96, v68, v96
	v_add_f32_e32 v116, v69, v96
	v_cvt_pk_bf16_f32 v148, v64, v65
	v_cvt_pk_bf16_f32 v149, v66, v67
	s_waitcnt lgkmcnt(4)
	v_mfma_scale_f32_32x32x64_f8f6f4 v[96:111], v[88:95], v[128:135], v[32:47], v242, v241 op_sel_hi:[0,0,0]
	ds_read_b64_tr_b16 v[64:65], v166 offset:45056
	ds_read_b64_tr_b16 v[66:67], v166 offset:45568
	v_add_f32_e32 v88, v70, v116
	v_add_f32_e32 v88, v71, v88
	v_add_f32_e32 v88, v72, v88
	v_add_f32_e32 v116, v73, v88
	v_cvt_pk_bf16_f32 v150, v68, v69
	v_cvt_pk_bf16_f32 v151, v70, v71
	s_waitcnt lgkmcnt(4)
	v_mfma_scale_f32_32x32x64_f8f6f4 v[80:95], v[80:87], v[128:135], v[32:47], v242, v241 op_sel_hi:[0,0,0]
	ds_read_b64_tr_b16 v[68:69], v166 offset:41984
	ds_read_b64_tr_b16 v[70:71], v166 offset:42496
	v_add_f32_e32 v116, v74, v116
	v_add_f32_e32 v116, v75, v116
	v_add_f32_e32 v116, v76, v116
	v_add_f32_e32 v116, v77, v116
	v_cvt_pk_bf16_f32 v144, v72, v73
	v_cvt_pk_bf16_f32 v145, v74, v75
	ds_read_b64_tr_b16 v[72:73], v166 offset:46080
	ds_read_b64_tr_b16 v[74:75], v166 offset:46592
	v_add_f32_e32 v116, v78, v116
	v_add_f32_e32 v116, v79, v116
	v_add_f32_e32 v116, v48, v116
	v_add_f32_e32 v116, v49, v116
	v_cvt_pk_bf16_f32 v146, v76, v77
	v_cvt_pk_bf16_f32 v147, v78, v79
	ds_read_b64_tr_b16 v[76:77], v166 offset:43008
	ds_read_b64_tr_b16 v[78:79], v166 offset:43520
	v_add_f32_e32 v116, v50, v116
	v_add_f32_e32 v116, v51, v116
	v_add_f32_e32 v116, v52, v116
	v_add_f32_e32 v116, v53, v116
	v_cvt_pk_bf16_f32 v140, v48, v49
	v_cvt_pk_bf16_f32 v141, v50, v51
	ds_read_b64_tr_b16 v[120:121], v166 offset:47104
	ds_read_b64_tr_b16 v[122:123], v166 offset:47616
	v_add_f32_e32 v48, v54, v116
	v_add_f32_e32 v48, v55, v48
	v_add_f32_e32 v48, v56, v48
	v_add_f32_e32 v48, v57, v48
	v_cvt_pk_bf16_f32 v142, v52, v53
	v_cvt_pk_bf16_f32 v143, v54, v55
	ds_read_b64_tr_b16 v[124:125], v166 offset:44032
	ds_read_b64_tr_b16 v[126:127], v166 offset:44544
	v_add_f32_e32 v48, v58, v48
	v_add_f32_e32 v48, v59, v48
	v_add_f32_e32 v48, v60, v48
	v_add_f32_e32 v48, v61, v48
	v_cvt_pk_bf16_f32 v136, v56, v57
	v_cvt_pk_bf16_f32 v137, v58, v59
	ds_read_b64_tr_b16 v[168:169], v166 offset:48128
	ds_read_b64_tr_b16 v[170:171], v166 offset:48640
	v_add_f32_e32 v48, v62, v48
	v_add_f32_e32 v48, v63, v48
	v_add_f32_e32 v48, 0, v48
	v_cvt_pk_bf16_f32 v138, v60, v61
	v_cvt_pk_bf16_f32 v139, v62, v63
	s_mov_b64 s[22:23], 0x1fc000
	v_add_f32_e32 v160, v118, v48
	s_add_i32 s10, s50, s29
	v_lshl_add_u64 v[48:49], v[154:155], 0, s[22:23]
	s_mov_b32 s11, m0
	s_mov_b32 m0, s10
	s_nop 0
	global_load_lds_dwordx4 v[48:49], off
	s_mov_b32 m0, s11
	s_mov_b64 s[10:11], 0x4728000
	s_cmp_lg_u32 0, -1
	v_lshl_add_u64 v[48:49], v[152:153], 0, s[10:11]
	s_cselect_b32 s10, 0, 0
	s_add_i32 s11, s10, s28
	s_add_i32 s22, s11, 0x8000
	s_mov_b32 s23, m0
	s_mov_b32 m0, s22
	s_nop 0
	global_load_lds_dwordx4 v[48:49], off
	s_mov_b32 m0, s23
	s_waitcnt lgkmcnt(14)
	v_mfma_f32_32x32x16_bf16 v[0:15], v[148:151], v[112:115], v[0:15]
	v_exp_f32_e32 v96, v96
	v_exp_f32_e32 v97, v97
	v_exp_f32_e32 v98, v98
	v_exp_f32_e32 v99, v99
	s_waitcnt lgkmcnt(12)
	v_mfma_f32_32x32x16_bf16 v[16:31], v[148:151], v[64:67], v[16:31]
	v_exp_f32_e32 v100, v100
	v_exp_f32_e32 v101, v101
	v_exp_f32_e32 v102, v102
	v_exp_f32_e32 v103, v103
	v_add_u32_e32 v60, s13, v165
	ds_read_b128 v[48:51], v60
	s_waitcnt lgkmcnt(11)
	v_mfma_f32_32x32x16_bf16 v[0:15], v[144:147], v[68:71], v[0:15]
	v_exp_f32_e32 v104, v104
	v_exp_f32_e32 v105, v105
	v_exp_f32_e32 v106, v106
	v_exp_f32_e32 v107, v107
	ds_read_b128 v[52:55], v60 offset:1024
	s_waitcnt lgkmcnt(10)
	v_mfma_f32_32x32x16_bf16 v[16:31], v[144:147], v[72:75], v[16:31]
	v_exp_f32_e32 v108, v108
	v_exp_f32_e32 v109, v109
	v_exp_f32_e32 v110, v110
	v_exp_f32_e32 v111, v111
	ds_read_b128 v[56:59], v60 offset:512
	s_waitcnt lgkmcnt(9)
	v_mfma_f32_32x32x16_bf16 v[0:15], v[140:143], v[76:79], v[0:15]
	v_exp_f32_e32 v80, v80
	v_exp_f32_e32 v81, v81
	v_exp_f32_e32 v82, v82
	v_exp_f32_e32 v83, v83
	ds_read_b128 v[60:63], v60 offset:1536
	s_waitcnt lgkmcnt(8)
	v_mfma_f32_32x32x16_bf16 v[16:31], v[140:143], v[120:123], v[16:31]
	v_exp_f32_e32 v84, v84
	v_exp_f32_e32 v85, v85
	v_exp_f32_e32 v86, v86
	v_exp_f32_e32 v87, v87
	s_waitcnt lgkmcnt(6)
	v_mfma_f32_32x32x16_bf16 v[0:15], v[136:139], v[124:127], v[0:15]
	v_exp_f32_e32 v88, v88
	v_exp_f32_e32 v89, v89
	v_exp_f32_e32 v90, v90
	v_exp_f32_e32 v91, v91
	s_waitcnt lgkmcnt(4)
	v_mfma_f32_32x32x16_bf16 v[16:31], v[136:139], v[168:171], v[16:31]
	v_exp_f32_e32 v92, v92
	v_exp_f32_e32 v93, v93
	v_exp_f32_e32 v94, v94
	v_exp_f32_e32 v95, v95
	s_waitcnt vmcnt(3) lgkmcnt(0)
	s_barrier
; #define WAIT_BAR(N) asm volatile("s_waitcnt vmcnt(" #N ") lgkmcnt(0)\n\ts_barrier":::"memory")
;   #define RESC() do{ if(resc){ asm volatile("s_waitcnt lgkmcnt(0)":::"memory"); \
;       _Pragma("unroll") for(int d_=0;d_<2;++d_) _Pragma("unroll") for(int r=0;r<16;++r)o[d_][r]*=wsf[crow(r,hi)]; } }while(0)
;   #define ROT() do{sl_prev=sl_cur;sl_cur=sl_next;sl_next=(sl_next==(NSLOT-1)*SLOTB)?0:sl_next+SLOTB;}while(0)
;   #define ENDW(tt) do{ if((tt)+3<NT){WAIT_BAR(3);} else if((tt)+2<NT){WAIT_BAR(2);} else {WAIT_BAR(0);} }while(0)
; #define WAIT_BAR(N) asm volatile("s_waitcnt vmcnt(" #N ") lgkmcnt(0)\n\ts_barrier":::"memory")
;   #define RESC() do{ if(resc){ asm volatile("s_waitcnt lgkmcnt(0)":::"memory"); \
;       _Pragma("unroll") for(int d_=0;d_<4;++d_) _Pragma("unroll") for(int r=0;r<16;++r)o[d_][r]*=wsf[crow(r,hi)]; } }while(0)
;   #define ROT() do{sl_prev=sl_cur;sl_cur=sl_next;sl_next=(sl_next==(NSLOT-1)*SLOTB)?0:sl_next+SLOTB;}while(0)
;   #define ENDW(tt) do{ if((tt)+3<NT){WAIT_BAR(5);} else if((tt)+2<NT){WAIT_BAR(4);} else {WAIT_BAR(0);} }while(0)
; #define WAIT_BAR(N) asm volatile("s_waitcnt vmcnt(" #N ") lgkmcnt(0)\n\ts_barrier":::"memory")
;   #define RESC() do{ if(resc){ asm volatile("s_waitcnt lgkmcnt(0)":::"memory"); \
;       _Pragma("unroll") for(int d_=0;d_<2;++d_) _Pragma("unroll") for(int r=0;r<16;++r)o[d_][r]*=wsf[crow(r,hi)]; } }while(0)
;   #define ROT() do{sl_prev=sl_cur;sl_cur=sl_next;sl_next=(sl_next==(NSLOT-1)*SLOTB)?0:sl_next+SLOTB;}while(0)
;   #define ENDW(tt) do{ if((tt)+3<NT){WAIT_BAR(3);} else if((tt)+2<NT){WAIT_BAR(2);} else {WAIT_BAR(0);} }while(0)
; template<int THRL,bool FIXED> __device__ __forceinline__ void attn_unit(int qb,const bf16*Qp,const unsigned char*__restrict__ K8h,const bf16*__restrict__ Vh,bf16*Op,int PO,char*shm){
;     ...
;   int t=1;
;     ...
;   for(;t+5<NT;t+=2){
;     STEP(pB0,pB1,pA0,pA1,t,true,true,true);     WAIT_BAR(3); RESC(); ROT();
;     STEP(pA0,pA1,pB0,pB1,t+1,true,true,true);   WAIT_BAR(3); RESC(); ROT();
;   }
;     ...
;   for(;t+1<NT;t+=2){
;     STEP(pB0,pB1,pA0,pA1,t,(t+3<NT),(t+2<NT),(t+1<NT));       ENDW(t);   RESC(); ROT();
;     STEP(pA0,pA1,pB0,pB1,t+1,(t+4<NT),(t+3<NT),(t+2<NT));     ENDW(t+1); RESC(); ROT();
	s_add_i32 s22, s13, 0x2000
	s_cmpk_lg_i32 s13, 0x4000
	s_cselect_b32 s22, s22, 0
	ds_read_b64_tr_b16 v[64:65], v166 offset:49152
	ds_read_b64_tr_b16 v[66:67], v166 offset:49664
	v_add_f32_e32 v68, v96, v97
	v_add_f32_e32 v68, v98, v68
	v_add_f32_e32 v68, v99, v68
	v_add_f32_e32 v68, v100, v68
	v_add_f32_e32 v72, v101, v68
	v_cvt_pk_bf16_f32 v148, v96, v97
	v_cvt_pk_bf16_f32 v149, v98, v99
	s_waitcnt lgkmcnt(4)
	v_mfma_scale_f32_32x32x64_f8f6f4 v[112:127], v[48:55], v[128:135], v[32:47], v242, v241 op_sel_hi:[0,0,0]
	ds_read_b64_tr_b16 v[68:69], v166 offset:53248
	ds_read_b64_tr_b16 v[70:71], v166 offset:53760
	v_add_f32_e32 v48, v102, v72
	v_add_f32_e32 v48, v103, v48
	v_add_f32_e32 v48, v104, v48
	v_add_f32_e32 v76, v105, v48
	s_waitcnt lgkmcnt(4)
	v_mfma_scale_f32_32x32x64_f8f6f4 v[48:63], v[56:63], v[128:135], v[32:47], v242, v241 op_sel_hi:[0,0,0]
	v_cvt_pk_bf16_f32 v150, v100, v101
	v_cvt_pk_bf16_f32 v151, v102, v103
	ds_read_b64_tr_b16 v[72:73], v166 offset:50176
	ds_read_b64_tr_b16 v[74:75], v166 offset:50688
	v_add_f32_e32 v76, v106, v76
	v_add_f32_e32 v76, v107, v76
	v_add_f32_e32 v76, v108, v76
	v_add_f32_e32 v96, v109, v76
	v_cvt_pk_bf16_f32 v144, v104, v105
	v_cvt_pk_bf16_f32 v145, v106, v107
	ds_read_b64_tr_b16 v[76:77], v166 offset:54272
	ds_read_b64_tr_b16 v[78:79], v166 offset:54784
	v_add_f32_e32 v96, v110, v96
	v_add_f32_e32 v96, v111, v96
	v_add_f32_e32 v96, v80, v96
	v_add_f32_e32 v100, v81, v96
	v_cvt_pk_bf16_f32 v146, v108, v109
	v_cvt_pk_bf16_f32 v147, v110, v111
	ds_read_b64_tr_b16 v[96:97], v166 offset:51200
	ds_read_b64_tr_b16 v[98:99], v166 offset:51712
	v_add_f32_e32 v100, v82, v100
	v_add_f32_e32 v100, v83, v100
	v_add_f32_e32 v100, v84, v100
	v_add_f32_e32 v100, v85, v100
	v_cvt_pk_bf16_f32 v140, v80, v81
	v_cvt_pk_bf16_f32 v141, v82, v83
	ds_read_b64_tr_b16 v[80:81], v166 offset:55296
	ds_read_b64_tr_b16 v[82:83], v166 offset:55808
	v_add_f32_e32 v100, v86, v100
	v_add_f32_e32 v100, v87, v100
	v_add_f32_e32 v100, v88, v100
	v_add_f32_e32 v100, v89, v100
	v_cvt_pk_bf16_f32 v142, v84, v85
	v_cvt_pk_bf16_f32 v143, v86, v87
	ds_read_b64_tr_b16 v[84:85], v166 offset:52224
	ds_read_b64_tr_b16 v[86:87], v166 offset:52736
	v_add_f32_e32 v100, v90, v100
	v_add_f32_e32 v100, v91, v100
	v_add_f32_e32 v100, v92, v100
	v_add_f32_e32 v100, v93, v100
	v_cvt_pk_bf16_f32 v136, v88, v89
	v_cvt_pk_bf16_f32 v137, v90, v91
	ds_read_b64_tr_b16 v[88:89], v166 offset:56320
	ds_read_b64_tr_b16 v[90:91], v166 offset:56832
	v_add_f32_e32 v100, v94, v100
	v_add_f32_e32 v100, v95, v100
	v_add_f32_e32 v100, 0, v100
	v_cvt_pk_bf16_f32 v138, v92, v93
	v_cvt_pk_bf16_f32 v139, v94, v95
	s_mov_b64 s[50:51], 0x1fe000
	s_add_i32 s13, s13, s29
	v_lshl_add_u64 v[92:93], v[154:155], 0, s[50:51]
	s_mov_b32 s23, m0
	s_mov_b32 m0, s13
	s_nop 0
	global_load_lds_dwordx4 v[92:93], off
	s_mov_b32 m0, s23
	v_lshl_add_u64 v[92:93], v[152:153], 0, s[42:43]
	s_add_i32 s11, s11, 0xa000
	s_mov_b32 s13, m0
	s_mov_b32 m0, s11
	s_nop 0
	global_load_lds_dwordx4 v[92:93], off
	s_mov_b32 m0, s13
	v_add_f32_e32 v160, v160, v100
	s_waitcnt lgkmcnt(14)
	v_mfma_f32_32x32x16_bf16 v[0:15], v[148:151], v[64:67], v[0:15]
	v_exp_f32_e32 v112, v112
	v_exp_f32_e32 v113, v113
	v_exp_f32_e32 v114, v114
	v_exp_f32_e32 v115, v115
	s_waitcnt lgkmcnt(12)
	v_mfma_f32_32x32x16_bf16 v[16:31], v[148:151], v[68:71], v[16:31]
	v_exp_f32_e32 v116, v116
	v_exp_f32_e32 v117, v117
	v_exp_f32_e32 v118, v118
	v_exp_f32_e32 v119, v119
	v_add_u32_e32 v92, s22, v165
	ds_read_b128 v[64:67], v92
	s_waitcnt lgkmcnt(11)
	v_mfma_f32_32x32x16_bf16 v[0:15], v[144:147], v[72:75], v[0:15]
	v_exp_f32_e32 v120, v120
	v_exp_f32_e32 v121, v121
	v_exp_f32_e32 v122, v122
	v_exp_f32_e32 v123, v123
	ds_read_b128 v[68:71], v92 offset:1024
	s_waitcnt lgkmcnt(10)
	v_mfma_f32_32x32x16_bf16 v[16:31], v[144:147], v[76:79], v[16:31]
	v_exp_f32_e32 v124, v124
	v_exp_f32_e32 v125, v125
	v_exp_f32_e32 v126, v126
	v_exp_f32_e32 v127, v127
	ds_read_b128 v[72:75], v92 offset:512
	s_waitcnt lgkmcnt(9)
	v_mfma_f32_32x32x16_bf16 v[0:15], v[140:143], v[96:99], v[0:15]
	v_exp_f32_e32 v48, v48
	v_exp_f32_e32 v49, v49
	v_exp_f32_e32 v50, v50
	v_exp_f32_e32 v51, v51
	ds_read_b128 v[76:79], v92 offset:1536
	s_waitcnt lgkmcnt(8)
	v_mfma_f32_32x32x16_bf16 v[16:31], v[140:143], v[80:83], v[16:31]
	v_exp_f32_e32 v52, v52
	v_exp_f32_e32 v53, v53
	v_exp_f32_e32 v54, v54
	v_exp_f32_e32 v55, v55
	s_waitcnt lgkmcnt(6)
	v_mfma_f32_32x32x16_bf16 v[0:15], v[136:139], v[84:87], v[0:15]
	v_exp_f32_e32 v56, v56
	v_exp_f32_e32 v57, v57
	v_exp_f32_e32 v58, v58
	v_exp_f32_e32 v59, v59
	s_waitcnt lgkmcnt(4)
	v_mfma_f32_32x32x16_bf16 v[16:31], v[136:139], v[88:91], v[16:31]
	v_exp_f32_e32 v60, v60
	v_exp_f32_e32 v61, v61
	v_exp_f32_e32 v62, v62
	v_exp_f32_e32 v63, v63
	s_waitcnt vmcnt(3) lgkmcnt(0)
	s_barrier
; #define WAIT_BAR(N) asm volatile("s_waitcnt vmcnt(" #N ") lgkmcnt(0)\n\ts_barrier":::"memory")
;   #define RESC() do{ if(resc){ asm volatile("s_waitcnt lgkmcnt(0)":::"memory"); \
;       _Pragma("unroll") for(int d_=0;d_<2;++d_) _Pragma("unroll") for(int r=0;r<16;++r)o[d_][r]*=wsf[crow(r,hi)]; } }while(0)
;   #define ROT() do{sl_prev=sl_cur;sl_cur=sl_next;sl_next=(sl_next==(NSLOT-1)*SLOTB)?0:sl_next+SLOTB;}while(0)
;   #define ENDW(tt) do{ if((tt)+3<NT){WAIT_BAR(3);} else if((tt)+2<NT){WAIT_BAR(2);} else {WAIT_BAR(0);} }while(0)
; #define WAIT_BAR(N) asm volatile("s_waitcnt vmcnt(" #N ") lgkmcnt(0)\n\ts_barrier":::"memory")
;   #define RESC() do{ if(resc){ asm volatile("s_waitcnt lgkmcnt(0)":::"memory"); \
;       _Pragma("unroll") for(int d_=0;d_<4;++d_) _Pragma("unroll") for(int r=0;r<16;++r)o[d_][r]*=wsf[crow(r,hi)]; } }while(0)
;   #define ROT() do{sl_prev=sl_cur;sl_cur=sl_next;sl_next=(sl_next==(NSLOT-1)*SLOTB)?0:sl_next+SLOTB;}while(0)
;   #define ENDW(tt) do{ if((tt)+3<NT){WAIT_BAR(5);} else if((tt)+2<NT){WAIT_BAR(4);} else {WAIT_BAR(0);} }while(0)
; #define WAIT_BAR(N) asm volatile("s_waitcnt vmcnt(" #N ") lgkmcnt(0)\n\ts_barrier":::"memory")
;   #define RESC() do{ if(resc){ asm volatile("s_waitcnt lgkmcnt(0)":::"memory"); \
;       _Pragma("unroll") for(int d_=0;d_<2;++d_) _Pragma("unroll") for(int r=0;r<16;++r)o[d_][r]*=wsf[crow(r,hi)]; } }while(0)
;   #define ROT() do{sl_prev=sl_cur;sl_cur=sl_next;sl_next=(sl_next==(NSLOT-1)*SLOTB)?0:sl_next+SLOTB;}while(0)
;   #define ENDW(tt) do{ if((tt)+3<NT){WAIT_BAR(3);} else if((tt)+2<NT){WAIT_BAR(2);} else {WAIT_BAR(0);} }while(0)
; template<int THRL,bool FIXED> __device__ __forceinline__ void attn_unit(int qb,const bf16*Qp,const unsigned char*__restrict__ K8h,const bf16*__restrict__ Vh,bf16*Op,int PO,char*shm){
;     ...
;   int t=1;
;     ...
;   for(;t+5<NT;t+=2){
;     STEP(pB0,pB1,pA0,pA1,t,true,true,true);     WAIT_BAR(3); RESC(); ROT();
;     STEP(pA0,pA1,pB0,pB1,t+1,true,true,true);   WAIT_BAR(3); RESC(); ROT();
;   }
;     ...
;   for(;t+1<NT;t+=2){
;     STEP(pB0,pB1,pA0,pA1,t,(t+3<NT),(t+2<NT),(t+1<NT));       ENDW(t);   RESC(); ROT();
;     STEP(pA0,pA1,pB0,pB1,t+1,(t+4<NT),(t+3<NT),(t+2<NT));     ENDW(t+1); RESC(); ROT();
	s_add_i32 s11, s22, 0x2000
	s_cmpk_lg_i32 s22, 0x4000
	s_cselect_b32 s11, s11, 0
	ds_read_b64_tr_b16 v[80:81], v166 offset:24576
	ds_read_b64_tr_b16 v[82:83], v166 offset:25088
	v_add_f32_e32 v84, v112, v113
	v_add_f32_e32 v84, v114, v84
	v_add_f32_e32 v84, v115, v84
	v_add_f32_e32 v84, v116, v84
	v_add_f32_e32 v88, v117, v84
	v_cvt_pk_bf16_f32 v148, v112, v113
	v_cvt_pk_bf16_f32 v149, v114, v115
	s_waitcnt lgkmcnt(4)
	v_mfma_scale_f32_32x32x64_f8f6f4 v[96:111], v[64:71], v[128:135], v[32:47], v242, v241 op_sel_hi:[0,0,0]
	ds_read_b64_tr_b16 v[84:85], v166 offset:28672
	ds_read_b64_tr_b16 v[86:87], v166 offset:29184
	v_add_f32_e32 v64, v118, v88
	v_add_f32_e32 v64, v119, v64
	v_add_f32_e32 v64, v120, v64
	v_add_f32_e32 v92, v121, v64
	v_cvt_pk_bf16_f32 v150, v116, v117
	v_cvt_pk_bf16_f32 v151, v118, v119
	s_waitcnt lgkmcnt(4)
	v_mfma_scale_f32_32x32x64_f8f6f4 v[64:79], v[72:79], v[128:135], v[32:47], v242, v241 op_sel_hi:[0,0,0]
	ds_read_b64_tr_b16 v[88:89], v166 offset:25600
	ds_read_b64_tr_b16 v[90:91], v166 offset:26112
	v_add_f32_e32 v92, v122, v92
	v_add_f32_e32 v92, v123, v92
	v_add_f32_e32 v92, v124, v92
	v_add_f32_e32 v112, v125, v92
	v_cvt_pk_bf16_f32 v144, v120, v121
	v_cvt_pk_bf16_f32 v145, v122, v123
	ds_read_b64_tr_b16 v[92:93], v166 offset:29696
	ds_read_b64_tr_b16 v[94:95], v166 offset:30208
	v_add_f32_e32 v112, v126, v112
	v_add_f32_e32 v112, v127, v112
	v_add_f32_e32 v112, v48, v112
	v_add_f32_e32 v116, v49, v112
	v_cvt_pk_bf16_f32 v146, v124, v125
	v_cvt_pk_bf16_f32 v147, v126, v127
	ds_read_b64_tr_b16 v[112:113], v166 offset:26624
	ds_read_b64_tr_b16 v[114:115], v166 offset:27136
	v_add_f32_e32 v116, v50, v116
	v_add_f32_e32 v116, v51, v116
	v_add_f32_e32 v116, v52, v116
	v_add_f32_e32 v120, v53, v116
	v_cvt_pk_bf16_f32 v140, v48, v49
	v_cvt_pk_bf16_f32 v141, v50, v51
	ds_read_b64_tr_b16 v[116:117], v166 offset:30720
	ds_read_b64_tr_b16 v[118:119], v166 offset:31232
	v_add_f32_e32 v48, v54, v120
	v_add_f32_e32 v48, v55, v48
	v_add_f32_e32 v48, v56, v48
	v_add_f32_e32 v48, v57, v48
	v_cvt_pk_bf16_f32 v142, v52, v53
	v_cvt_pk_bf16_f32 v143, v54, v55
	ds_read_b64_tr_b16 v[120:121], v166 offset:27648
	ds_read_b64_tr_b16 v[122:123], v166 offset:28160
	v_add_f32_e32 v48, v58, v48
	v_add_f32_e32 v48, v59, v48
	v_add_f32_e32 v48, v60, v48
	v_add_f32_e32 v48, v61, v48
	v_cvt_pk_bf16_f32 v136, v56, v57
	v_cvt_pk_bf16_f32 v137, v58, v59
	ds_read_b64_tr_b16 v[124:125], v166 offset:31744
	ds_read_b64_tr_b16 v[126:127], v166 offset:32256
	v_add_f32_e32 v48, v62, v48
	v_add_f32_e32 v48, v63, v48
	v_add_f32_e32 v48, 0, v48
	v_cvt_pk_bf16_f32 v138, v60, v61
	v_cvt_pk_bf16_f32 v139, v62, v63
	s_add_i32 s10, s10, 0xc000
	v_add_f32_e32 v160, v160, v48
	v_lshl_add_u64 v[48:49], v[152:153], 0, s[46:47]
	s_add_i32 s28, s28, s10
	s_mov_b32 s13, m0
	s_mov_b32 m0, s28
	s_nop 0
	global_load_lds_dwordx4 v[48:49], off
	s_mov_b32 m0, s13
	s_waitcnt lgkmcnt(14)
	v_mfma_f32_32x32x16_bf16 v[0:15], v[148:151], v[80:83], v[0:15]
	v_exp_f32_e32 v96, v96
	v_exp_f32_e32 v97, v97
	v_exp_f32_e32 v98, v98
	v_exp_f32_e32 v99, v99
	s_waitcnt lgkmcnt(12)
	v_mfma_f32_32x32x16_bf16 v[16:31], v[148:151], v[84:87], v[16:31]
	v_exp_f32_e32 v100, v100
	v_exp_f32_e32 v101, v101
	v_exp_f32_e32 v102, v102
	v_exp_f32_e32 v103, v103
	v_add_u32_e32 v60, s11, v165
	ds_read_b128 v[48:51], v60
	s_waitcnt lgkmcnt(11)
	v_mfma_f32_32x32x16_bf16 v[0:15], v[144:147], v[88:91], v[0:15]
	v_exp_f32_e32 v104, v104
	v_exp_f32_e32 v105, v105
	v_exp_f32_e32 v106, v106
	v_exp_f32_e32 v107, v107
	ds_read_b128 v[52:55], v60 offset:1024
	s_waitcnt lgkmcnt(10)
	v_mfma_f32_32x32x16_bf16 v[16:31], v[144:147], v[92:95], v[16:31]
	v_exp_f32_e32 v108, v108
	v_exp_f32_e32 v109, v109
	v_exp_f32_e32 v110, v110
	v_exp_f32_e32 v111, v111
	ds_read_b128 v[56:59], v60 offset:512
	s_waitcnt lgkmcnt(9)
	v_mfma_f32_32x32x16_bf16 v[0:15], v[140:143], v[112:115], v[0:15]
	v_exp_f32_e32 v64, v64
	v_exp_f32_e32 v65, v65
	v_exp_f32_e32 v66, v66
	v_exp_f32_e32 v67, v67
	ds_read_b128 v[60:63], v60 offset:1536
	s_waitcnt lgkmcnt(8)
	v_mfma_f32_32x32x16_bf16 v[16:31], v[140:143], v[116:119], v[16:31]
	v_exp_f32_e32 v68, v68
	v_exp_f32_e32 v69, v69
	v_exp_f32_e32 v70, v70
	v_exp_f32_e32 v71, v71
	s_waitcnt lgkmcnt(6)
	v_mfma_f32_32x32x16_bf16 v[0:15], v[136:139], v[120:123], v[0:15]
	v_exp_f32_e32 v72, v72
	v_exp_f32_e32 v73, v73
	v_exp_f32_e32 v74, v74
	v_exp_f32_e32 v75, v75
	s_waitcnt lgkmcnt(4)
	v_mfma_f32_32x32x16_bf16 v[16:31], v[136:139], v[124:127], v[16:31]
	v_exp_f32_e32 v76, v76
	v_exp_f32_e32 v77, v77
	v_exp_f32_e32 v78, v78
	v_exp_f32_e32 v79, v79
	s_waitcnt vmcnt(2) lgkmcnt(0)
	s_barrier
;   #define RESC() do{ if(resc){ asm volatile("s_waitcnt lgkmcnt(0)":::"memory"); \
;       _Pragma("unroll") for(int d_=0;d_<2;++d_) _Pragma("unroll") for(int r=0;r<16;++r)o[d_][r]*=wsf[crow(r,hi)]; } }while(0)
;   #define ROT() do{sl_prev=sl_cur;sl_cur=sl_next;sl_next=(sl_next==(NSLOT-1)*SLOTB)?0:sl_next+SLOTB;}while(0)
;   #define ENDW(tt) do{ if((tt)+3<NT){WAIT_BAR(3);} else if((tt)+2<NT){WAIT_BAR(2);} else {WAIT_BAR(0);} }while(0)
;   #define RESC() do{ if(resc){ asm volatile("s_waitcnt lgkmcnt(0)":::"memory"); \
;       _Pragma("unroll") for(int d_=0;d_<4;++d_) _Pragma("unroll") for(int r=0;r<16;++r)o[d_][r]*=wsf[crow(r,hi)]; } }while(0)
;   #define ROT() do{sl_prev=sl_cur;sl_cur=sl_next;sl_next=(sl_next==(NSLOT-1)*SLOTB)?0:sl_next+SLOTB;}while(0)
;   #define ENDW(tt) do{ if((tt)+3<NT){WAIT_BAR(5);} else if((tt)+2<NT){WAIT_BAR(4);} else {WAIT_BAR(0);} }while(0)
;   #define RESC() do{ if(resc){ asm volatile("s_waitcnt lgkmcnt(0)":::"memory"); \
;       _Pragma("unroll") for(int d_=0;d_<2;++d_) _Pragma("unroll") for(int r=0;r<16;++r)o[d_][r]*=wsf[crow(r,hi)]; } }while(0)
;   #define ROT() do{sl_prev=sl_cur;sl_cur=sl_next;sl_next=(sl_next==(NSLOT-1)*SLOTB)?0:sl_next+SLOTB;}while(0)
;   #define ENDW(tt) do{ if((tt)+3<NT){WAIT_BAR(3);} else if((tt)+2<NT){WAIT_BAR(2);} else {WAIT_BAR(0);} }while(0)
; template<int THRL,bool FIXED> __device__ __forceinline__ void attn_unit(int qb,const bf16*Qp,const unsigned char*__restrict__ K8h,const bf16*__restrict__ Vh,bf16*Op,int PO,char*shm){
;     ...
;   for(;t+1<NT;t+=2){
;     STEP(pB0,pB1,pA0,pA1,t,(t+3<NT),(t+2<NT),(t+1<NT));       ENDW(t);   RESC(); ROT();
;     STEP(pA0,pA1,pB0,pB1,t+1,(t+4<NT),(t+3<NT),(t+2<NT));     ENDW(t+1); RESC(); ROT();
	s_add_i32 s13, s11, 0x2000
	s_cmpk_lg_i32 s11, 0x4000
	s_cselect_b32 s11, s13, 0
	ds_read_b64_tr_b16 v[112:113], v166 offset:32768
	ds_read_b64_tr_b16 v[114:115], v166 offset:33280
	v_add_f32_e32 v80, v96, v97
	v_add_f32_e32 v80, v98, v80
	v_add_f32_e32 v80, v99, v80
	v_add_f32_e32 v80, v100, v80
	v_add_f32_e32 v116, v101, v80
	v_cvt_pk_bf16_f32 v148, v96, v97
	v_cvt_pk_bf16_f32 v149, v98, v99
	s_waitcnt lgkmcnt(4)
	v_mfma_scale_f32_32x32x64_f8f6f4 v[80:95], v[48:55], v[128:135], v[32:47], v242, v241 op_sel_hi:[0,0,0]
	ds_read_b64_tr_b16 v[96:97], v166 offset:36864
	ds_read_b64_tr_b16 v[98:99], v166 offset:37376
	v_add_f32_e32 v48, v102, v116
	v_add_f32_e32 v48, v103, v48
	v_add_f32_e32 v48, v104, v48
	v_add_f32_e32 v116, v105, v48
	s_waitcnt lgkmcnt(4)
	v_mfma_scale_f32_32x32x64_f8f6f4 v[48:63], v[56:63], v[128:135], v[32:47], v242, v241 op_sel_hi:[0,0,0]
	v_cvt_pk_bf16_f32 v150, v100, v101
	v_cvt_pk_bf16_f32 v151, v102, v103
	ds_read_b64_tr_b16 v[100:101], v166 offset:33792
	ds_read_b64_tr_b16 v[102:103], v166 offset:34304
	v_add_f32_e32 v116, v106, v116
	v_add_f32_e32 v116, v107, v116
	v_add_f32_e32 v116, v108, v116
	v_add_f32_e32 v120, v109, v116
	v_cvt_pk_bf16_f32 v144, v104, v105
	v_cvt_pk_bf16_f32 v145, v106, v107
	ds_read_b64_tr_b16 v[116:117], v166 offset:37888
	ds_read_b64_tr_b16 v[118:119], v166 offset:38400
	v_add_f32_e32 v104, v110, v120
	v_add_f32_e32 v104, v111, v104
	v_add_f32_e32 v104, v64, v104
	v_add_f32_e32 v104, v65, v104
	v_cvt_pk_bf16_f32 v146, v108, v109
	v_cvt_pk_bf16_f32 v147, v110, v111
	ds_read_b64_tr_b16 v[120:121], v166 offset:34816
	ds_read_b64_tr_b16 v[122:123], v166 offset:35328
	v_add_f32_e32 v104, v66, v104
	v_add_f32_e32 v104, v67, v104
	v_add_f32_e32 v104, v68, v104
	v_add_f32_e32 v104, v69, v104
	v_cvt_pk_bf16_f32 v140, v64, v65
	v_cvt_pk_bf16_f32 v141, v66, v67
	ds_read_b64_tr_b16 v[124:125], v166 offset:38912
	ds_read_b64_tr_b16 v[126:127], v166 offset:39424
	v_add_f32_e32 v64, v70, v104
	v_add_f32_e32 v64, v71, v64
	v_add_f32_e32 v64, v72, v64
	v_add_f32_e32 v64, v73, v64
	v_cvt_pk_bf16_f32 v142, v68, v69
	v_cvt_pk_bf16_f32 v143, v70, v71
	ds_read_b64_tr_b16 v[152:153], v166 offset:35840
	ds_read_b64_tr_b16 v[154:155], v166 offset:36352
	v_add_f32_e32 v64, v74, v64
	v_add_f32_e32 v64, v75, v64
	v_add_f32_e32 v64, v76, v64
	v_add_f32_e32 v64, v77, v64
	v_cvt_pk_bf16_f32 v136, v72, v73
	v_cvt_pk_bf16_f32 v137, v74, v75
	ds_read_b64_tr_b16 v[72:73], v166 offset:39936
	ds_read_b64_tr_b16 v[74:75], v166 offset:40448
	v_add_f32_e32 v64, v78, v64
	v_add_f32_e32 v64, v79, v64
	v_add_f32_e32 v64, 0, v64
	v_cvt_pk_bf16_f32 v138, v76, v77
	v_cvt_pk_bf16_f32 v139, v78, v79
	s_nop 0
	v_add_f32_e32 v104, v160, v64
	s_waitcnt lgkmcnt(14)
	v_mfma_f32_32x32x16_bf16 v[0:15], v[148:151], v[112:115], v[0:15]
	v_exp_f32_e32 v80, v80
	v_exp_f32_e32 v81, v81
	v_exp_f32_e32 v82, v82
	v_exp_f32_e32 v83, v83
	s_waitcnt lgkmcnt(12)
	v_mfma_f32_32x32x16_bf16 v[16:31], v[148:151], v[96:99], v[16:31]
	v_exp_f32_e32 v84, v84
	v_exp_f32_e32 v85, v85
	v_exp_f32_e32 v86, v86
	v_exp_f32_e32 v87, v87
	v_add_u32_e32 v76, s11, v165
	ds_read_b128 v[64:67], v76
	s_waitcnt lgkmcnt(11)
	v_mfma_f32_32x32x16_bf16 v[0:15], v[144:147], v[100:103], v[0:15]
	v_exp_f32_e32 v88, v88
	v_exp_f32_e32 v89, v89
	v_exp_f32_e32 v90, v90
	v_exp_f32_e32 v91, v91
	ds_read_b128 v[68:71], v76 offset:1024
	s_waitcnt lgkmcnt(10)
	v_mfma_f32_32x32x16_bf16 v[16:31], v[144:147], v[116:119], v[16:31]
	v_exp_f32_e32 v92, v92
	v_exp_f32_e32 v93, v93
	v_exp_f32_e32 v94, v94
	v_exp_f32_e32 v95, v95
	ds_read_b128 v[106:109], v76 offset:512
	s_waitcnt lgkmcnt(9)
	v_mfma_f32_32x32x16_bf16 v[0:15], v[140:143], v[120:123], v[0:15]
	v_exp_f32_e32 v48, v48
	v_exp_f32_e32 v49, v49
	v_exp_f32_e32 v50, v50
	v_exp_f32_e32 v51, v51
	ds_read_b128 v[110:113], v76 offset:1536
	s_waitcnt lgkmcnt(8)
	v_mfma_f32_32x32x16_bf16 v[16:31], v[140:143], v[124:127], v[16:31]
	v_exp_f32_e32 v52, v52
	v_exp_f32_e32 v53, v53
	v_exp_f32_e32 v54, v54
	v_exp_f32_e32 v55, v55
	s_waitcnt lgkmcnt(6)
	v_mfma_f32_32x32x16_bf16 v[0:15], v[136:139], v[152:155], v[0:15]
	v_exp_f32_e32 v56, v56
	v_exp_f32_e32 v57, v57
	v_exp_f32_e32 v58, v58
	v_exp_f32_e32 v59, v59
	s_waitcnt lgkmcnt(4)
	v_mfma_f32_32x32x16_bf16 v[16:31], v[136:139], v[72:75], v[16:31]
	v_exp_f32_e32 v60, v60
	v_exp_f32_e32 v61, v61
	v_exp_f32_e32 v62, v62
	v_exp_f32_e32 v63, v63
	s_waitcnt vmcnt(0) lgkmcnt(0)
	s_barrier
; #define SBAR() __builtin_amdgcn_sched_barrier(0)
;   #define RESC() do{ if(resc){ asm volatile("s_waitcnt lgkmcnt(0)":::"memory"); \
;       _Pragma("unroll") for(int d_=0;d_<2;++d_) _Pragma("unroll") for(int r=0;r<16;++r)o[d_][r]*=wsf[crow(r,hi)]; } }while(0)
;   #define PKW(P,B) cvtpk_s(P[B],P[B+1])
; #define SBAR() __builtin_amdgcn_sched_barrier(0)
;   #define RESC() do{ if(resc){ asm volatile("s_waitcnt lgkmcnt(0)":::"memory"); \
;       _Pragma("unroll") for(int d_=0;d_<4;++d_) _Pragma("unroll") for(int r=0;r<16;++r)o[d_][r]*=wsf[crow(r,hi)]; } }while(0)
;   #define PKW(P,B) cvtpk_s(P[B],P[B+1])
; #define SBAR() __builtin_amdgcn_sched_barrier(0)
;   #define RESC() do{ if(resc){ asm volatile("s_waitcnt lgkmcnt(0)":::"memory"); \
;       _Pragma("unroll") for(int d_=0;d_<2;++d_) _Pragma("unroll") for(int r=0;r<16;++r)o[d_][r]*=wsf[crow(r,hi)]; } }while(0)
; __device__ __forceinline__ void pv(f32x16*o,int vb,bf16x8 pa0,bf16x8 pa1,bf16x8 pa2,bf16x8 pa3){
;   #pragma unroll
;   for(int d0=0;d0<2;++d0){s16x4 lo[4],hi[4];
;     #pragma unroll
;     for(int ks=0;ks<4;++ks){
;       asm volatile("ds_read_b64_tr_b16 %0,%1 offset:%c2":"=&v"(lo[ks]):"v"(vb),"i"(d0*4096+ks*1024):"memory");
;       asm volatile("ds_read_b64_tr_b16 %0,%1 offset:%c2":"=&v"(hi[ks]):"v"(vb),"i"(d0*4096+ks*1024+512):"memory");}
;     asm volatile("s_waitcnt lgkmcnt(0)":::"memory");SBAR();
;     ...
;     o[d0]=__builtin_amdgcn_mfma_f32_32x32x16_bf16(pa0,PK(0),o[d0],0,0,0);
;     o[d0]=__builtin_amdgcn_mfma_f32_32x32x16_bf16(pa1,PK(1),o[d0],0,0,0);
;     o[d0]=__builtin_amdgcn_mfma_f32_32x32x16_bf16(pa2,PK(2),o[d0],0,0,0);
;     o[d0]=__builtin_amdgcn_mfma_f32_32x32x16_bf16(pa3,PK(3),o[d0],0,0,0);
;     ...
;   }
; }
; template<int THRL,bool FIXED> __device__ __forceinline__ void attn_unit(int qb,const bf16*Qp,const unsigned char*__restrict__ K8h,const bf16*__restrict__ Vh,bf16*Op,int PO,char*shm){
;     ...
;   STEP(pB0,pB1,pA0,pA1,NT-1,false,false,false); RESC();
;   { float sacc=pB0[0]+pB0[1]; _Pragma("unroll") for(int r=2;r<16;++r)sacc+=pB0[r]; _Pragma("unroll") for(int r=0;r<16;++r)sacc+=pB1[r]; l_reg+=sacc;
;     pw0=(u32x4){PKW(pB0,0),PKW(pB0,2),PKW(pB0,4),PKW(pB0,6)};pw1=(u32x4){PKW(pB0,8),PKW(pB0,10),PKW(pB0,12),PKW(pB0,14)};pw2=(u32x4){PKW(pB1,0),PKW(pB1,2),PKW(pB1,4),PKW(pB1,6)};pw3=(u32x4){PKW(pB1,8),PKW(pB1,10),PKW(pB1,12),PKW(pB1,14)};
;     SBAR(); pv(o,vb0+VSL(NT-1),PAF(0),PAF(1),PAF(2),PAF(3)); }
	ds_read_b64_tr_b16 v[96:97], v166 offset:40960
	ds_read_b64_tr_b16 v[98:99], v166 offset:41472
	v_add_f32_e32 v72, v80, v81
	v_add_f32_e32 v72, v82, v72
	v_add_f32_e32 v72, v83, v72
	v_add_f32_e32 v72, v84, v72
	v_add_f32_e32 v100, v85, v72
	v_cvt_pk_bf16_f32 v148, v80, v81
	v_cvt_pk_bf16_f32 v149, v82, v83
	s_waitcnt lgkmcnt(4)
	v_mfma_scale_f32_32x32x64_f8f6f4 v[64:79], v[64:71], v[128:135], v[32:47], v242, v241 op_sel_hi:[0,0,0]
	ds_read_b64_tr_b16 v[80:81], v166 offset:45056
	ds_read_b64_tr_b16 v[82:83], v166 offset:45568
	s_waitcnt lgkmcnt(4)
	v_mfma_scale_f32_32x32x64_f8f6f4 v[32:47], v[106:113], v[128:135], v[32:47], v242, v241 op_sel_hi:[0,0,0]
	v_add_f32_e32 v100, v86, v100
	v_add_f32_e32 v100, v87, v100
	v_add_f32_e32 v100, v88, v100
	v_add_f32_e32 v105, v89, v100
	v_cvt_pk_bf16_f32 v150, v84, v85
	v_cvt_pk_bf16_f32 v151, v86, v87
	ds_read_b64_tr_b16 v[100:101], v166 offset:41984
	ds_read_b64_tr_b16 v[102:103], v166 offset:42496
	v_add_f32_e32 v84, v90, v105
	v_add_f32_e32 v84, v91, v84
	v_add_f32_e32 v84, v92, v84
	v_add_f32_e32 v105, v93, v84
	v_cvt_pk_bf16_f32 v144, v88, v89
	v_cvt_pk_bf16_f32 v145, v90, v91
	ds_read_b64_tr_b16 v[84:85], v166 offset:46080
	ds_read_b64_tr_b16 v[86:87], v166 offset:46592
	v_add_f32_e32 v88, v94, v105
	v_add_f32_e32 v88, v95, v88
	v_add_f32_e32 v88, v48, v88
	v_add_f32_e32 v105, v49, v88
	v_cvt_pk_bf16_f32 v146, v92, v93
	v_cvt_pk_bf16_f32 v147, v94, v95
	ds_read_b64_tr_b16 v[88:89], v166 offset:43008
	ds_read_b64_tr_b16 v[90:91], v166 offset:43520
	v_add_f32_e32 v92, v50, v105
	v_add_f32_e32 v92, v51, v92
	v_add_f32_e32 v92, v52, v92
	v_add_f32_e32 v92, v53, v92
	v_cvt_pk_bf16_f32 v140, v48, v49
	v_cvt_pk_bf16_f32 v141, v50, v51
	ds_read_b64_tr_b16 v[48:49], v166 offset:47104
	ds_read_b64_tr_b16 v[50:51], v166 offset:47616
	v_add_f32_e32 v92, v54, v92
	v_add_f32_e32 v92, v55, v92
	v_add_f32_e32 v92, v56, v92
	v_add_f32_e32 v105, v57, v92
	v_cvt_pk_bf16_f32 v142, v52, v53
	v_cvt_pk_bf16_f32 v143, v54, v55
	ds_read_b64_tr_b16 v[92:93], v166 offset:44032
	ds_read_b64_tr_b16 v[94:95], v166 offset:44544
	v_add_f32_e32 v52, v58, v105
	v_add_f32_e32 v52, v59, v52
	v_add_f32_e32 v52, v60, v52
	v_add_f32_e32 v105, v61, v52
	v_cvt_pk_bf16_f32 v136, v56, v57
	v_cvt_pk_bf16_f32 v137, v58, v59
	ds_read_b64_tr_b16 v[52:53], v166 offset:48128
	ds_read_b64_tr_b16 v[54:55], v166 offset:48640
	v_add_f32_e32 v56, v62, v105
	v_add_f32_e32 v56, v63, v56
	v_add_f32_e32 v56, 0, v56
	v_cvt_pk_bf16_f32 v138, v60, v61
	v_cvt_pk_bf16_f32 v139, v62, v63
	v_exp_f32_e32 v64, v64
	v_exp_f32_e32 v65, v65
	v_exp_f32_e32 v66, v66
	v_exp_f32_e32 v67, v67
	s_nop 0
	v_exp_f32_e32 v68, v68
	v_exp_f32_e32 v69, v69
	v_exp_f32_e32 v70, v70
	v_exp_f32_e32 v71, v71
	s_nop 0
	v_exp_f32_e32 v72, v72
	v_exp_f32_e32 v73, v73
	v_exp_f32_e32 v74, v74
	v_exp_f32_e32 v75, v75
	s_nop 0
	v_exp_f32_e32 v76, v76
	v_exp_f32_e32 v77, v77
	v_exp_f32_e32 v78, v78
	v_exp_f32_e32 v79, v79
	v_exp_f32_e32 v32, v32
	v_exp_f32_e32 v33, v33
	v_exp_f32_e32 v34, v34
	v_exp_f32_e32 v35, v35
	s_nop 0
	v_exp_f32_e32 v36, v36
	v_exp_f32_e32 v37, v37
	v_exp_f32_e32 v38, v38
	v_exp_f32_e32 v39, v39
	s_nop 0
	v_exp_f32_e32 v40, v40
	v_exp_f32_e32 v41, v41
	v_exp_f32_e32 v42, v42
	v_exp_f32_e32 v43, v43
	s_nop 0
	v_exp_f32_e32 v44, v44
	v_exp_f32_e32 v45, v45
	v_exp_f32_e32 v46, v46
	v_exp_f32_e32 v47, v47
	s_waitcnt lgkmcnt(14)
	v_mfma_f32_32x32x16_bf16 v[0:15], v[148:151], v[96:99], v[0:15]
	v_add_f32_e32 v57, v64, v65
	v_add_f32_e32 v57, v66, v57
	v_add_f32_e32 v57, v67, v57
	v_add_f32_e32 v57, v68, v57
	v_add_f32_e32 v57, v69, v57
	v_add_f32_e32 v57, v70, v57
	v_add_f32_e32 v57, v71, v57
	s_waitcnt lgkmcnt(12)
	v_mfma_f32_32x32x16_bf16 v[16:31], v[148:151], v[80:83], v[16:31]
	v_add_f32_e32 v57, v72, v57
	v_add_f32_e32 v57, v73, v57
	v_add_f32_e32 v57, v74, v57
	v_add_f32_e32 v57, v75, v57
	v_add_f32_e32 v57, v76, v57
	v_add_f32_e32 v57, v77, v57
	v_add_f32_e32 v57, v78, v57
	s_waitcnt lgkmcnt(10)
	v_mfma_f32_32x32x16_bf16 v[0:15], v[144:147], v[100:103], v[0:15]
	v_add_f32_e32 v57, v79, v57
	v_add_f32_e32 v57, v32, v57
	v_add_f32_e32 v57, v33, v57
	v_add_f32_e32 v57, v34, v57
	v_add_f32_e32 v57, v35, v57
	v_add_f32_e32 v57, v36, v57
	v_add_f32_e32 v57, v37, v57
	s_waitcnt lgkmcnt(8)
	v_mfma_f32_32x32x16_bf16 v[16:31], v[144:147], v[84:87], v[16:31]
	v_add_f32_e32 v57, v38, v57
	v_add_f32_e32 v57, v39, v57
	v_add_f32_e32 v57, v40, v57
	v_add_f32_e32 v57, v41, v57
	v_add_f32_e32 v57, v42, v57
	v_add_f32_e32 v57, v43, v57
	v_add_f32_e32 v57, v44, v57
	s_waitcnt lgkmcnt(6)
	v_mfma_f32_32x32x16_bf16 v[0:15], v[140:143], v[88:91], v[0:15]
	v_add_f32_e32 v57, v45, v57
	v_add_f32_e32 v57, v46, v57
	v_add_f32_e32 v57, v47, v57
	v_add_f32_e32 v56, v104, v56
	v_add_f32_e32 v56, v56, v57
	v_cvt_pk_bf16_f32 v32, v32, v33
	v_cvt_pk_bf16_f32 v58, v64, v65
	s_waitcnt lgkmcnt(4)
	v_mfma_f32_32x32x16_bf16 v[16:31], v[140:143], v[48:51], v[16:31]
	v_cvt_pk_bf16_f32 v59, v66, v67
	v_cvt_pk_bf16_f32 v60, v68, v69
	v_cvt_pk_bf16_f32 v61, v70, v71
	v_cvt_pk_bf16_f32 v62, v72, v73
	v_cvt_pk_bf16_f32 v63, v74, v75
	v_cvt_pk_bf16_f32 v64, v76, v77
	v_cvt_pk_bf16_f32 v65, v78, v79
	s_waitcnt lgkmcnt(2)
	v_mfma_f32_32x32x16_bf16 v[0:15], v[136:139], v[92:95], v[0:15]
	v_cvt_pk_bf16_f32 v33, v34, v35
	v_cvt_pk_bf16_f32 v34, v36, v37
	v_cvt_pk_bf16_f32 v35, v38, v39
	v_cvt_pk_bf16_f32 v36, v40, v41
	v_cvt_pk_bf16_f32 v37, v42, v43
	v_cvt_pk_bf16_f32 v38, v44, v45
	v_cvt_pk_bf16_f32 v39, v46, v47
	s_waitcnt lgkmcnt(0)
	v_mfma_f32_32x32x16_bf16 v[16:31], v[136:139], v[52:55], v[16:31]
	v_add_u32_e32 v40, s10, v163
	v_add3_u32 v57, v40, v162, v164
	ds_read_b64_tr_b16 v[40:41],v57 offset:0
	ds_read_b64_tr_b16 v[42:43],v57 offset:512
	ds_read_b64_tr_b16 v[44:45],v57 offset:1024
	ds_read_b64_tr_b16 v[46:47],v57 offset:1536
	ds_read_b64_tr_b16 v[48:49],v57 offset:2048
	ds_read_b64_tr_b16 v[50:51],v57 offset:2560
	ds_read_b64_tr_b16 v[52:53],v57 offset:3072
	ds_read_b64_tr_b16 v[54:55],v57 offset:3584
	s_waitcnt lgkmcnt(0)
	s_nop 0
	v_mfma_f32_32x32x16_bf16 v[0:15], v[58:61], v[40:43], v[0:15]
	ds_read_b64_tr_b16 v[40:41],v57 offset:4096
	ds_read_b64_tr_b16 v[42:43],v57 offset:4608
	v_mfma_f32_32x32x16_bf16 v[0:15], v[62:65], v[44:47], v[0:15]
	ds_read_b64_tr_b16 v[44:45],v57 offset:5120
	ds_read_b64_tr_b16 v[46:47],v57 offset:5632
	v_mfma_f32_32x32x16_bf16 v[0:15], v[32:35], v[48:51], v[0:15]
	ds_read_b64_tr_b16 v[48:49],v57 offset:6144
	ds_read_b64_tr_b16 v[50:51],v57 offset:6656
	v_mfma_f32_32x32x16_bf16 v[0:15], v[36:39], v[52:55], v[0:15]
	ds_read_b64_tr_b16 v[52:53],v57 offset:7168
	ds_read_b64_tr_b16 v[54:55],v57 offset:7680
	s_waitcnt lgkmcnt(0)
	v_mfma_f32_32x32x16_bf16 v[16:31], v[58:61], v[40:43], v[16:31]
	v_cmp_gt_u32_e32 vcc, 32, v156
	v_mfma_f32_32x32x16_bf16 v[16:31], v[62:65], v[44:47], v[16:31]
	v_mfma_f32_32x32x16_bf16 v[16:31], v[32:35], v[48:51], v[16:31]
	v_mov_b32_e32 v32, v56
	s_nop 1
	v_permlane32_swap_b32_e32 v56, v32
	v_mfma_f32_32x32x16_bf16 v[16:31], v[36:39], v[52:55], v[16:31]
	s_and_saveexec_b64 s[10:11], vcc
	s_cbranch_execz .LBB0_541
; template<int THRL,bool FIXED> __device__ __forceinline__ void attn_unit(int qb,const bf16*Qp,const unsigned char*__restrict__ K8h,const bf16*__restrict__ Vh,bf16*Op,int PO,char*shm){
;     ...
;   {auto rr=__builtin_amdgcn_permlane32_swap(__float_as_uint(l_reg),__float_as_uint(l_reg),false,false);l_reg=__uint_as_float(rr[0])+__uint_as_float(rr[1]);}
;   if(hi==0)wsf[32+r32]=l_reg;asm volatile("s_waitcnt lgkmcnt(0)":::"memory");
	v_lshl_add_u32 v33, v158, 2, s12
	v_add_f32_e32 v32, v56, v32
	ds_write_b32 v33, v32 offset:57472
	s_branch .LBB0_541
